# grid barrier: waiters poll the top-level arrival counter (target = (generation+1) * XCDs) instead of the generation word bumped after the last arrival atomic returns
# speedup vs baseline: 1.0051x; 1.0039x over previous
.LBB0_84:
	s_or_b64 exec, exec, s[14:15]
	buffer_inv sc1
	v_cvt_f32_u32_e32 v1, v4
	s_waitcnt vmcnt(1)
	v_readfirstlane_b32 s3, v5
	v_sub_u32_e32 v5, 0, v4
	v_rcp_iflag_f32_e32 v1, v1
	v_add_u32_e32 v6, s3, v3
	v_mul_f32_e32 v1, 0x4f7ffffe, v1
	v_cvt_u32_f32_e32 v1, v1
	v_mul_lo_u32 v3, v5, v1
	v_mul_hi_u32 v3, v1, v3
	v_add_u32_e32 v1, v1, v3
	v_mul_hi_u32 v1, v6, v1
	v_mul_lo_u32 v3, v1, v4
	v_sub_u32_e32 v3, v6, v3
	v_add_u32_e32 v5, 1, v1
	v_cmp_ge_u32_e32 vcc, v3, v4
	s_nop 1
	v_cndmask_b32_e32 v1, v1, v5, vcc
	v_sub_u32_e32 v5, v3, v4
	v_cndmask_b32_e32 v3, v3, v5, vcc
	v_add_u32_e32 v5, 1, v1
	v_cmp_ge_u32_e32 vcc, v3, v4
	s_nop 1
	v_cndmask_b32_e32 v3, v1, v5, vcc
	v_mul_lo_u32 v5, v4, v3
	v_add_u32_e32 v1, 1, v6
	v_add_u32_e32 v4, v5, v4
	v_cmp_ne_u32_e32 vcc, v1, v4
	s_and_saveexec_b64 s[6:7], vcc
	s_xor_b64 s[12:13], exec, s[6:7]
	s_cbranch_execz .LBB0_98
	v_mad_u32_u24 v6, v3, v2, v2
	v_mov_b32_e32 v1, 0
	s_add_u32 s18, s88, 0x4500
	s_addc_u32 s19, s89, 0
	global_load_dword v1, v1, s[18:19] offset:-256 sc1
	s_waitcnt vmcnt(0)
	v_cmp_lt_u32_e32 vcc, v1, v6
	s_and_saveexec_b64 s[14:15], vcc
	s_cbranch_execz .LBB0_97
	s_add_u32 s16, s88, 0x1200
	s_addc_u32 s17, s89, 0
	s_mov_b32 s3, 1
	s_mov_b64 s[20:21], 0
	s_waitcnt lgkmcnt(0)
	v_mov_b32_e32 v2, 0
	s_branch .LBB0_88

.LBB0_92:
	global_load_dword v1, v2, s[18:19] offset:-256 sc1
	s_add_i32 s3, s3, 1
	s_mov_b64 s[26:27], -1
	s_waitcnt vmcnt(0)
	v_cmp_ge_u32_e32 vcc, v1, v6
	s_orn2_b64 s[24:25], vcc, exec
	s_branch .LBB0_87

.LBB0_101:
	s_or_b64 exec, exec, s[14:15]
	v_cvt_f32_u32_e32 v1, v2
	s_waitcnt vmcnt(0)
	v_readfirstlane_b32 s3, v4
	v_sub_u32_e32 v4, 0, v2
	s_add_u32 s14, s88, 0x4500
	v_rcp_iflag_f32_e32 v1, v1
	v_add_u32_e32 v3, s3, v3
	v_add_u32_e32 v5, 1, v3
	s_addc_u32 s15, s89, 0
	v_mul_f32_e32 v1, 0x4f7ffffe, v1
	v_cvt_u32_f32_e32 v1, v1
	s_mov_b64 s[16:17], -1
	v_mul_lo_u32 v4, v4, v1
	v_mul_hi_u32 v4, v1, v4
	v_add_u32_e32 v1, v1, v4
	v_mul_hi_u32 v1, v3, v1
	v_mul_lo_u32 v4, v1, v2
	v_sub_u32_e32 v3, v3, v4
	v_add_u32_e32 v6, 1, v1
	v_cmp_ge_u32_e32 vcc, v3, v2
	v_sub_u32_e32 v4, v3, v2
	s_nop 0
	v_cndmask_b32_e32 v1, v1, v6, vcc
	v_cndmask_b32_e32 v3, v3, v4, vcc
	v_add_u32_e32 v4, 1, v1
	v_cmp_ge_u32_e32 vcc, v3, v2
	s_nop 1
	v_cndmask_b32_e32 v4, v1, v4, vcc
	v_mul_lo_u32 v1, v2, v4
	v_add_u32_e32 v1, v1, v2
	v_cmp_ne_u32_e32 vcc, v5, v1
	v_mov_b32_e32 v6, v1
	v_mov_b64_e32 v[2:3], s[14:15]
	s_and_saveexec_b64 s[12:13], vcc
	s_cbranch_execz .LBB0_113
	v_mov_b32_e32 v2, 0
	global_load_dword v1, v2, s[14:15] offset:-256 sc1
	s_mov_b64 s[20:21], 0
	s_waitcnt vmcnt(0)
	v_cmp_lt_u32_e32 vcc, v1, v6
	s_and_saveexec_b64 s[18:19], vcc
	s_cbranch_execz .LBB0_112
	s_add_u32 s16, s88, 0x1200
	s_addc_u32 s17, s89, 0
	s_mov_b32 s3, 1
	s_branch .LBB0_105

.LBB0_109:
	global_load_dword v1, v2, s[14:15] offset:-256 sc1
	s_add_i32 s3, s3, 1
	s_mov_b64 s[24:25], -1
	s_waitcnt vmcnt(0)
	v_cmp_ge_u32_e32 vcc, v1, v6
	s_orn2_b64 s[28:29], vcc, exec
	s_branch .LBB0_104

.LBB0_166:
	s_or_b64 exec, exec, s[12:13]
	buffer_inv sc1
	v_cvt_f32_u32_e32 v1, v4
	s_waitcnt vmcnt(1)
	v_readfirstlane_b32 s3, v5
	v_sub_u32_e32 v5, 0, v4
	v_rcp_iflag_f32_e32 v1, v1
	v_add_u32_e32 v6, s3, v3
	v_mul_f32_e32 v1, 0x4f7ffffe, v1
	v_cvt_u32_f32_e32 v1, v1
	v_mul_lo_u32 v3, v5, v1
	v_mul_hi_u32 v3, v1, v3
	v_add_u32_e32 v1, v1, v3
	v_mul_hi_u32 v1, v6, v1
	v_mul_lo_u32 v3, v1, v4
	v_sub_u32_e32 v3, v6, v3
	v_add_u32_e32 v5, 1, v1
	v_cmp_ge_u32_e32 vcc, v3, v4
	s_nop 1
	v_cndmask_b32_e32 v1, v1, v5, vcc
	v_sub_u32_e32 v5, v3, v4
	v_cndmask_b32_e32 v3, v3, v5, vcc
	v_add_u32_e32 v5, 1, v1
	v_cmp_ge_u32_e32 vcc, v3, v4
	s_nop 1
	v_cndmask_b32_e32 v3, v1, v5, vcc
	v_mul_lo_u32 v5, v4, v3
	v_add_u32_e32 v1, 1, v6
	v_add_u32_e32 v4, v5, v4
	v_cmp_ne_u32_e32 vcc, v1, v4
	s_and_saveexec_b64 s[6:7], vcc
	s_xor_b64 s[10:11], exec, s[6:7]
	s_cbranch_execz .LBB0_180
	v_mad_u32_u24 v6, v3, v2, v2
	v_mov_b32_e32 v1, 0
	s_add_u32 s16, s88, 0x4500
	s_addc_u32 s17, s89, 0
	global_load_dword v1, v1, s[16:17] offset:-256 sc1
	s_waitcnt vmcnt(0)
	v_cmp_lt_u32_e32 vcc, v1, v6
	s_and_saveexec_b64 s[12:13], vcc
	s_cbranch_execz .LBB0_179
	s_add_u32 s14, s88, 0x1200
	s_addc_u32 s15, s89, 0
	s_mov_b32 s3, 1
	s_mov_b64 s[18:19], 0
	s_waitcnt lgkmcnt(0)
	v_mov_b32_e32 v2, 0
	s_branch .LBB0_170

.LBB0_174:
	global_load_dword v1, v2, s[16:17] offset:-256 sc1
	s_add_i32 s3, s3, 1
	s_mov_b64 s[24:25], -1
	s_waitcnt vmcnt(0)
	v_cmp_ge_u32_e32 vcc, v1, v6
	s_orn2_b64 s[22:23], vcc, exec
	s_branch .LBB0_169

.LBB0_183:
	s_or_b64 exec, exec, s[12:13]
	v_cvt_f32_u32_e32 v1, v2
	s_waitcnt vmcnt(0)
	v_readfirstlane_b32 s3, v4
	v_sub_u32_e32 v4, 0, v2
	s_add_u32 s12, s88, 0x4500
	v_rcp_iflag_f32_e32 v1, v1
	v_add_u32_e32 v3, s3, v3
	v_add_u32_e32 v5, 1, v3
	s_addc_u32 s13, s89, 0
	v_mul_f32_e32 v1, 0x4f7ffffe, v1
	v_cvt_u32_f32_e32 v1, v1
	s_mov_b64 s[14:15], -1
	v_mul_lo_u32 v4, v4, v1
	v_mul_hi_u32 v4, v1, v4
	v_add_u32_e32 v1, v1, v4
	v_mul_hi_u32 v1, v3, v1
	v_mul_lo_u32 v4, v1, v2
	v_sub_u32_e32 v3, v3, v4
	v_add_u32_e32 v6, 1, v1
	v_cmp_ge_u32_e32 vcc, v3, v2
	v_sub_u32_e32 v4, v3, v2
	s_nop 0
	v_cndmask_b32_e32 v1, v1, v6, vcc
	v_cndmask_b32_e32 v3, v3, v4, vcc
	v_add_u32_e32 v4, 1, v1
	v_cmp_ge_u32_e32 vcc, v3, v2
	s_nop 1
	v_cndmask_b32_e32 v4, v1, v4, vcc
	v_mul_lo_u32 v1, v2, v4
	v_add_u32_e32 v1, v1, v2
	v_cmp_ne_u32_e32 vcc, v5, v1
	v_mov_b32_e32 v6, v1
	v_mov_b64_e32 v[2:3], s[12:13]
	s_and_saveexec_b64 s[10:11], vcc
	s_cbranch_execz .LBB0_195
	v_mov_b32_e32 v2, 0
	global_load_dword v1, v2, s[12:13] offset:-256 sc1
	s_mov_b64 s[18:19], 0
	s_waitcnt vmcnt(0)
	v_cmp_lt_u32_e32 vcc, v1, v6
	s_and_saveexec_b64 s[16:17], vcc
	s_cbranch_execz .LBB0_194
	s_add_u32 s14, s88, 0x1200
	s_addc_u32 s15, s89, 0
	s_mov_b32 s3, 1
	s_branch .LBB0_187

.LBB0_191:
	global_load_dword v1, v2, s[12:13] offset:-256 sc1
	s_add_i32 s3, s3, 1
	s_mov_b64 s[22:23], -1
	s_waitcnt vmcnt(0)
	v_cmp_ge_u32_e32 vcc, v1, v6
	s_orn2_b64 s[26:27], vcc, exec
	s_branch .LBB0_186
